# RWKV loop: loop-invariant address arithmetic hoisted (step-C array bases, post row pointer), state copy pair removed
# baseline (speedup 1.0000x reference)
.LBB0_421:
	s_or_b64 exec, exec, s[18:19]
	s_mul_i32 s52, s36, 0x20800
	s_xor_b64 s[76:77], s[22:23], -1
	s_lshl_b64 s[18:19], s[52:53], 2
	s_add_u32 s18, s20, s18
	v_mov_b32_e32 v6, 0xc200
	v_mov_b32_e32 v7, 0xb000
	s_addc_u32 s19, s21, s19
	v_cndmask_b32_e64 v6, v6, v7, s[16:17]
	s_lshl_b32 s16, s34, 1
	s_add_u32 s20, s20, s16
	s_addc_u32 s21, s21, 0
	s_lshl_b32 s22, s35, 2
	s_add_u32 s18, s18, s22
	s_addc_u32 s19, s19, 0
	s_add_u32 s78, s18, 0x118000
	v_readlane_b32 s18, v255, 3
	v_lshlrev_b32_e32 v4, 1, v116
	s_addc_u32 s79, s19, 0
	v_lshl_add_u32 v61, v235, 2, s18
	s_lshl_b32 s18, s37, 1
	v_and_b32_e32 v5, 14, v4
	v_lshrrev_b32_e32 v7, 2, v116
	s_add_u32 s18, s20, s18
	v_and_b32_e32 v52, 16, v7
	s_addc_u32 s19, s21, 0
	v_lshlrev_b32_e32 v16, 1, v5
	v_ashrrev_i32_e32 v87, 4, v116
	v_add_u32_e32 v64, 0, v4
	v_lshlrev_b32_e32 v67, 5, v5
	v_lshl_add_u64 v[4:5], s[18:19], 0, v[16:17]
	v_lshlrev_b32_e32 v16, 8, v52
	v_lshl_or_b32 v69, v139, 10, v16
	v_lshl_or_b32 v16, v87, 8, v122
	v_add_u32_e32 v92, 16, v87
	v_and_b32_e32 v60, 1, v116
	v_add_u32_e32 v91, 0, v16
	v_lshl_or_b32 v16, v92, 8, v122
	v_add_u32_e32 v93, 0, v16
	v_add_u32_e32 v16, 0x11200, v64
	v_cmp_eq_u32_e32 vcc, 0, v60
	v_or_b32_e32 v7, v52, v140
	v_mul_u32_u24_e32 v7, 0x90, v7
	v_cndmask_b32_e32 v98, v61, v16, vcc
	v_add_u32_e32 v16, 0x11000, v64
	v_cndmask_b32_e32 v99, v61, v16, vcc
	v_add_u32_e32 v16, 0x10e00, v64
	v_cndmask_b32_e32 v100, v61, v16, vcc
	v_add_u32_e32 v16, 0x10c00, v64
	v_cndmask_b32_e32 v101, v61, v16, vcc
	v_add_u32_e32 v16, 0x10a00, v64
	s_mov_b64 s[18:19], 0xe488000
	v_cndmask_b32_e32 v102, v61, v16, vcc
	v_add_u32_e32 v16, 0x10800, v64
	v_add3_u32 v62, 0, v6, v7
	v_or_b32_e32 v6, s38, v140
	v_lshl_add_u64 v[18:19], v[4:5], 0, s[18:19]
	s_mov_b32 s18, 0x5040100
	s_movk_i32 s20, 0xffde
	v_add_u32_e32 v97, v106, v105
	v_cndmask_b32_e32 v103, v61, v16, vcc
	v_add_u32_e32 v16, 0x10600, v64
	v_cmp_eq_u32_e64 s[16:17], 0, v6
	v_perm_b32 v7, v153, v151, s18
	v_perm_b32 v6, v149, v147, s18
	v_perm_b32 v5, v145, v143, s18
	v_perm_b32 v4, v142, v141, s18
	v_perm_b32 v11, v165, v163, s18
	v_perm_b32 v10, v162, v161, s18
	v_perm_b32 v9, v160, v159, s18
	v_perm_b32 v8, v158, v157, s18
	v_perm_b32 v15, v186, v184, s18
	v_perm_b32 v14, v182, v180, s18
	v_perm_b32 v13, v178, v176, s18
	v_perm_b32 v12, v174, v173, s18
	v_perm_b32 v27, v198, v195, s18
	v_perm_b32 v26, v194, v193, s18
	v_perm_b32 v25, v192, v191, s18
	v_perm_b32 v24, v190, v189, s18
	v_perm_b32 v35, v156, v155, s18
	v_perm_b32 v34, v154, v152, s18
	v_perm_b32 v33, v150, v148, s18
	v_perm_b32 v32, v146, v144, s18
	v_perm_b32 v39, v172, v171, s18
	v_perm_b32 v38, v170, v169, s18
	v_perm_b32 v37, v168, v167, s18
	v_perm_b32 v36, v166, v164, s18
	v_perm_b32 v43, v188, v187, s18
	v_perm_b32 v42, v185, v183, s18
	v_perm_b32 v41, v181, v179, s18
	v_perm_b32 v40, v177, v175, s18
	v_perm_b32 v47, v204, v203, s18
	v_perm_b32 v46, v202, v201, s18
	v_perm_b32 v45, v200, v199, s18
	v_perm_b32 v44, v197, v196, s18
	v_mad_u64_u32 v[58:59], s[18:19], v97, s20, v[104:105]
	v_cndmask_b32_e32 v104, v61, v16, vcc
	v_add_u32_e32 v16, 0x10400, v64
	v_cndmask_b32_e32 v105, v61, v16, vcc
	v_add_u32_e32 v16, 0x10200, v64
	v_cndmask_b32_e32 v106, v61, v16, vcc
	v_add_u32_e32 v16, 0x10000, v64
	v_cndmask_b32_e32 v107, v61, v16, vcc
	v_add_u32_e32 v16, 0xfe00, v64
	v_cndmask_b32_e32 v108, v61, v16, vcc
	v_add_u32_e32 v16, 0xfc00, v64
	v_cndmask_b32_e32 v109, v61, v16, vcc
	v_add_u32_e32 v16, 0xfa00, v64
	v_cndmask_b32_e32 v110, v61, v16, vcc
	v_add_u32_e32 v16, 0xf800, v64
	v_cndmask_b32_e32 v111, v61, v16, vcc
	v_add_u32_e32 v16, 0xf600, v64
	v_cndmask_b32_e32 v112, v61, v16, vcc
	v_add_u32_e32 v16, 0xf400, v64
	v_cndmask_b32_e32 v113, v61, v16, vcc
	v_add_u32_e32 v16, 0xf200, v64
	v_cndmask_b32_e32 v114, v61, v16, vcc
	v_add_u32_e32 v16, 0xf000, v64
	v_add_u32_e32 v94, v206, v205
	v_cndmask_b32_e32 v115, v61, v16, vcc
	v_add_u32_e32 v16, 0xee00, v64
	v_and_b32_e32 v63, 48, v116
	v_ashrrev_i32_e32 v90, 3, v116
	v_mad_u64_u32 v[52:53], s[18:19], v94, s20, v[116:117]
	v_cndmask_b32_e32 v116, v61, v16, vcc
	v_add_u32_e32 v16, 0xec00, v64
	v_add_u32_e32 v95, v234, v233
	v_cndmask_b32_e32 v122, v61, v16, vcc
	v_add_u32_e32 v16, 0xea00, v64
	v_mad_u64_u32 v[54:55], s[18:19], v95, s20, v[124:125]
	v_add_u32_e32 v96, v237, v236
	v_cndmask_b32_e32 v124, v61, v16, vcc
	v_add_u32_e32 v16, 0xe800, v64
	v_mad_u64_u32 v[56:57], s[18:19], v96, s20, v[126:127]
	v_cndmask_b32_e32 v126, v61, v16, vcc
	v_add_u32_e32 v16, 0xe600, v64
	v_lshl_add_u32 v88, v140, 4, 0
	v_cndmask_b32_e32 v139, v61, v16, vcc
	v_add_u32_e32 v16, 0xe400, v64
	v_mad_i32_i24 v68, v140, -12, v88
	v_cndmask_b32_e32 v140, v61, v16, vcc
	v_add_u32_e32 v16, 0xe200, v64
	v_cndmask_b32_e32 v141, v61, v16, vcc
	v_add_u32_e32 v16, 0xe000, v64
	v_cndmask_b32_e32 v142, v61, v16, vcc
	v_add_u32_e32 v16, 0xde00, v64
	v_cndmask_b32_e32 v143, v61, v16, vcc
	v_add_u32_e32 v16, 0xdc00, v64
	v_cndmask_b32_e32 v144, v61, v16, vcc
	v_add_u32_e32 v16, 0xda00, v64
	v_cndmask_b32_e32 v145, v61, v16, vcc
	v_add_u32_e32 v16, 0xd800, v64
	v_cndmask_b32_e32 v146, v61, v16, vcc
	v_add_u32_e32 v16, 0xd600, v64
	v_cndmask_b32_e32 v147, v61, v16, vcc
	v_and_b32_e32 v16, -16, v52
	v_add_u32_e32 v65, 0xd400, v64
	v_cmp_ne_u32_e64 s[18:19], 16, v16
	v_lshl_add_u32 v16, v94, 6, 0
	v_lshlrev_b32_e32 v53, 5, v52
	s_mov_b32 s28, 0x9c00
	s_movk_i32 s29, 0xc0
	s_movk_i32 s30, 0xff90
	v_cndmask_b32_e32 v148, v61, v65, vcc
	v_add3_u32 v55, v16, v53, s28
	v_mad_u64_u32 v[60:61], s[20:21], v94, s29, v[16:17]
	v_mul_lo_u32 v16, v94, s30
	v_lshlrev_b32_e32 v59, 4, v52
	v_add3_u32 v59, v60, v16, v59
	v_and_b32_e32 v16, -16, v54
	v_cmp_ne_u32_e64 s[20:21], 16, v16
	v_lshl_add_u32 v16, v95, 6, 0
	v_add_u32_e32 v53, v60, v53
	v_lshlrev_b32_e32 v64, 5, v54
	v_mad_u64_u32 v[60:61], s[22:23], v95, s29, v[16:17]
	v_add3_u32 v65, v16, v64, s28
	v_mul_lo_u32 v16, v95, s30
	v_lshlrev_b32_e32 v61, 4, v54
	v_add3_u32 v71, v60, v16, v61
	v_and_b32_e32 v16, -16, v56
	v_cmp_ne_u32_e64 s[22:23], 16, v16
	v_lshl_add_u32 v16, v96, 6, 0
	v_add_u32_e32 v64, v60, v64
	v_lshlrev_b32_e32 v72, 5, v56
	v_mad_u64_u32 v[60:61], s[24:25], v96, s29, v[16:17]
	v_add3_u32 v82, v16, v72, s28
	v_mul_lo_u32 v16, v96, s30
	v_lshlrev_b32_e32 v61, 4, v56
	v_add3_u32 v158, v60, v16, v61
	v_and_b32_e32 v16, -16, v58
	v_cmp_ne_u32_e64 s[24:25], 16, v16
	v_lshl_add_u32 v16, v97, 6, 0
	v_add_u32_e32 v83, v60, v72
	v_lshlrev_b32_e32 v72, 5, v58
	v_mad_u64_u32 v[60:61], s[26:27], v97, s29, v[16:17]
	v_add3_u32 v152, v16, v72, s28
	v_mul_lo_u32 v16, v97, s30
	v_lshlrev_b32_e32 v61, 4, v58
	v_add3_u32 v159, v60, v16, v61
	v_lshl_add_u32 v16, v86, 6, 0
	v_add_u32_e32 v153, v60, v72
	v_lshlrev_b32_e32 v72, 5, v84
	v_mad_u64_u32 v[60:61], s[26:27], v86, s29, v[16:17]
	v_add3_u32 v155, v16, v72, s28
	v_add_u32_e32 v16, v60, v72
	v_mul_lo_u32 v61, v86, s30
	v_lshlrev_b32_e32 v72, 4, v84
	v_mov_b32_e32 v149, s40
	v_mov_b32_e32 v150, s41
	v_cmp_gt_u32_e64 s[26:27], 32, v52
	v_add3_u32 v160, v60, v61, v72
	v_mov_b32_e32 v80, s42
	v_mov_b32_e32 v81, s34
	v_cmp_gt_i32_e32 vcc, 8, v52
	v_cndmask_b32_e64 v61, v149, v150, s[26:27]
	v_mov_b32_e32 v151, s39
	v_cmp_gt_u32_e64 s[26:27], 24, v52
	v_cndmask_b32_e32 v60, v80, v81, vcc
	v_cmp_gt_i32_e64 s[28:29], 16, v52
	v_cndmask_b32_e64 v61, v61, v151, s[26:27]
	v_cmp_gt_u32_e64 s[30:31], 32, v54
	v_cndmask_b32_e64 v60, v61, v60, s[28:29]
	v_lshl_add_u32 v60, v52, 3, v60
	v_ashrrev_i32_e32 v61, 31, v60
	v_lshl_add_u64 v[72:73], v[60:61], 1, s[58:59]
	v_cmp_gt_i32_e64 s[28:29], 8, v54
	v_cndmask_b32_e64 v61, v149, v150, s[30:31]
	v_cmp_gt_u32_e64 s[30:31], 24, v54
	v_cndmask_b32_e64 v60, v80, v81, s[28:29]
	v_cmp_gt_i32_e64 s[34:35], 16, v54
	v_cndmask_b32_e64 v61, v61, v151, s[30:31]
	v_cmp_gt_u32_e64 s[36:37], 32, v56
	v_cndmask_b32_e64 v60, v61, v60, s[34:35]
	v_lshl_add_u32 v60, v54, 3, v60
	v_ashrrev_i32_e32 v61, 31, v60
	v_lshl_add_u64 v[74:75], v[60:61], 1, s[58:59]
	v_cmp_gt_i32_e64 s[34:35], 8, v56
	v_cndmask_b32_e64 v61, v149, v150, s[36:37]
	v_cmp_gt_u32_e64 s[36:37], 24, v56
	v_cndmask_b32_e64 v60, v80, v81, s[34:35]
	v_cmp_gt_i32_e64 s[38:39], 16, v56
	v_cndmask_b32_e64 v61, v61, v151, s[36:37]
	v_cmp_gt_u32_e64 s[40:41], 32, v58
	v_cndmask_b32_e64 v60, v61, v60, s[38:39]
	v_lshl_add_u32 v60, v56, 3, v60
	v_ashrrev_i32_e32 v61, 31, v60
	v_lshl_add_u64 v[76:77], v[60:61], 1, s[58:59]
	v_cmp_gt_i32_e64 s[38:39], 8, v58
	v_cndmask_b32_e64 v61, v149, v150, s[40:41]
	v_cmp_gt_u32_e64 s[40:41], 24, v58
	v_cndmask_b32_e64 v60, v80, v81, s[38:39]
	v_cmp_gt_i32_e64 s[42:43], 16, v58
	v_cndmask_b32_e64 v61, v61, v151, s[40:41]
	v_cmp_gt_u32_e64 s[44:45], 32, v84
	v_cndmask_b32_e64 v60, v61, v60, s[42:43]
	v_lshl_add_u32 v60, v58, 3, v60
	v_ashrrev_i32_e32 v61, 31, v60
	v_lshl_add_u64 v[78:79], v[60:61], 1, s[58:59]
	v_cmp_gt_i32_e64 s[42:43], 8, v84
	v_cndmask_b32_e64 v61, v149, v150, s[44:45]
	v_cmp_gt_u32_e64 s[44:45], 24, v84
	v_cndmask_b32_e64 v60, v80, v81, s[42:43]
	v_cmp_gt_i32_e64 s[48:49], 16, v84
	v_cndmask_b32_e64 v61, v61, v151, s[44:45]
	v_add_u32_e32 v57, 0x1f00, v53
	v_cndmask_b32_e64 v60, v61, v60, s[48:49]
	v_cmp_gt_u32_e64 s[48:49], 16, v52
	v_add_u32_e32 v70, 0x1f00, v64
	v_add_u32_e32 v85, 0x1f00, v83
	v_cndmask_b32_e64 v52, v55, v57, s[48:49]
	v_cndmask_b32_e32 v149, v52, v53, vcc
	v_cmp_gt_u32_e32 vcc, 16, v54
	v_add_u32_e32 v154, 0x1f00, v153
	v_add_u32_e32 v156, 0x1f00, v16
	v_cndmask_b32_e32 v53, v65, v70, vcc
	v_cmp_gt_u32_e32 vcc, 16, v56
	v_lshl_add_u32 v60, v84, 3, v60
	v_mov_b32_e32 v57, 0xc080
	v_cndmask_b32_e32 v54, v82, v85, vcc
	v_cmp_gt_u32_e32 vcc, 16, v58
	v_lshl_add_u32 v66, v90, 9, 0
	v_ashrrev_i32_e32 v61, 31, v60
	v_cndmask_b32_e32 v55, v152, v154, vcc
	v_cmp_gt_u32_e32 vcc, 16, v84
	v_cndmask_b32_e64 v52, v57, v254, s[26:27]
	v_cndmask_b32_e64 v150, v53, v64, s[28:29]
	v_cndmask_b32_e32 v56, v155, v156, vcc
	v_cndmask_b32_e64 v53, v57, v254, s[30:31]
	v_cndmask_b32_e64 v151, v54, v83, s[34:35]
	v_cndmask_b32_e64 v54, v57, v254, s[36:37]
	v_cndmask_b32_e64 v152, v55, v153, s[38:39]
	v_cndmask_b32_e64 v55, v57, v254, s[40:41]
	v_cndmask_b32_e64 v153, v56, v16, s[42:43]
	v_cndmask_b32_e64 v56, v57, v254, s[44:45]
	v_mov_b32_e32 v16, v17
	v_lshl_add_u32 v89, v87, 2, 0
	v_lshl_add_u64 v[80:81], v[60:61], 1, s[58:59]
	s_mov_b32 s34, -8
	v_add_u32_e32 v154, v62, v63
	v_add_u32_e32 v155, v66, v67
	v_add_u32_e32 v156, v59, v52
	v_add_u32_e32 v157, v71, v53
	v_add_u32_e32 v158, v158, v54
	v_add_u32_e32 v159, v159, v55
	v_add_u32_e32 v160, v160, v56
	v_add_u32_e32 v161, v68, v69
	v_mov_b64_e32 v[82:83], v[16:17]
	v_mov_b64_e32 v[84:85], v[16:17]
	v_mov_b32_e32 v52, v232
	v_mov_b32_e32 v53, v231
	v_mov_b32_e32 v54, v230
	v_mov_b32_e32 v55, v207
	s_waitcnt lgkmcnt(0)
	s_barrier
	v_mad_u64_u32 v[218:219], s[26:27], v94, s83, v[72:73]
	v_mad_u64_u32 v[220:221], s[26:27], v95, s83, v[74:75]
	v_mad_u64_u32 v[222:223], s[26:27], v96, s83, v[76:77]
	v_mad_u64_u32 v[244:245], s[26:27], v97, s83, v[78:79]
	v_mad_u64_u32 v[246:247], s[26:27], v86, s83, v[80:81]
	v_and_b32_e32 v98, 31, v119
	v_lshlrev_b32_e32 v98, 3, v98
	v_lshrrev_b32_e32 v99, 5, v119
	s_lshl_b32 s26, s32, 3
	v_add_u32_e32 v99, s26, v99
	v_lshl_add_u32 v99, v99, 2, v228
	v_add_u32_e32 v99, 0x6000, v99
	v_lshrrev_b32_e32 v100, 1, v119
	v_lshlrev_b32_e32 v100, 2, v100
	v_add_u32_e32 v100, 0xd400, v100
	v_lshrrev_b32_e32 v101, 3, v119
	v_lshlrev_b32_e32 v101, 9, v101
	v_and_b32_e32 v102, 7, v119
	v_lshl_add_u32 v101, v102, 6, v101
	v_add_u32_e32 v101, 0xd400, v101
	v_sub_u32_e32 v102, s26, v102
	v_lshlrev_b32_e32 v102, 1, v102
	v_ashrrev_i32_e32 v103, 31, v102
	v_lshl_add_u64 v[102:103], v[18:19], 0, v[102:103]
	s_load_dwordx2 s[26:27], s[84:85], 0x120
	v_lshrrev_b32_e32 v60, 3, v119
	v_and_b32_e32 v61, 7, v119
	v_mov_b32_e32 v62, s82
	v_add_u32_e32 v62, 0xffffff80, v62
	v_bfe_u32 v63, v62, 2, 3
	v_lshlrev_b32_e32 v63, 6, v63
	v_lshrrev_b32_e32 v64, 5, v62
	v_lshlrev_b32_e32 v64, 6, v64
	v_and_b32_e32 v65, 3, v62
	v_lshlrev_b32_e32 v65, 4, v65
	v_lshl_add_u32 v66, v61, 3, v63
	v_lshl_add_u32 v67, v61, 3, v64
	v_add_u32_e32 v67, 0x600, v67
	v_and_b32_e32 v68, 1, v119
	v_lshl_add_u32 v69, v68, 3, v63
	v_add_u32_e32 v69, v69, v65
	v_add_u32_e32 v69, 0x400, v69
	v_mul_u32_u24_e32 v70, 0x1200, v60
	v_lshrrev_b32_e32 v71, 1, v119
	v_mul_u32_u24_e32 v162, 0x1200, v71
	s_waitcnt lgkmcnt(0)
	s_add_u32 s26, s26, 0x6aa8000
	s_addc_u32 s27, s27, 0
	v_lshl_add_u32 v16, v66, 1, v70
	v_lshl_add_u64 v[218:219], v[16:17], 0, s[26:27]
	v_add_u32_e32 v16, 0x400, v16
	v_lshl_add_u64 v[220:221], v[16:17], 0, s[26:27]
	v_lshl_add_u32 v16, v67, 1, v70
	v_lshl_add_u64 v[222:223], v[16:17], 0, s[26:27]
	v_add_u32_e32 v16, 0x100, v16
	v_lshl_add_u64 v[244:245], v[16:17], 0, s[26:27]
	v_lshl_add_u32 v16, v69, 1, v162
	v_lshl_add_u64 v[246:247], v[16:17], 0, s[26:27]
	v_lshlrev_b32_e32 v149, 8, v60
	v_lshl_add_u32 v149, v61, 5, v149
	v_add_u32_e32 v150, 0x2000, v149
	v_mul_u32_u24_e32 v156, 0x90, v60
	v_lshl_add_u32 v156, v61, 4, v156
	v_add_u32_e32 v156, 0xb000, v156
	v_add_u32_e32 v157, 0x1200, v156
	v_lshlrev_b32_e32 v151, 6, v71
	v_lshl_add_u32 v151, v68, 5, v151
	v_add_u32_e32 v151, 0xa000, v151
	v_mul_f32_e32 v117, s73, v117
	v_mul_f32_e32 v121, s73, v121
	v_mul_f32_e32 v123, s73, v123
	v_mul_f32_e32 v125, s73, v125
	v_add_u32_e32 v153, 0x100, v98
	v_add_u32_e32 v152, 0x8000, v161
	v_add_u32_e32 v158, 0x4000, v161
	v_add_u32_e32 v230, 0x2000, v91
	v_add_u32_e32 v231, 0x8000, v91
	v_add_u32_e32 v232, 0x6000, v91
	v_add_u32_e32 v233, 0x2000, v93
	v_add_u32_e32 v234, 0x8000, v93
	v_add_u32_e32 v235, 0x6000, v93
	v_lshlrev_b32_e32 v16, 10, v90
	v_lshl_add_u64 v[236:237], v[16:17], 0, v[102:103]
	s_branch .LBB0_424

.LBB0_423:
	s_waitcnt lgkmcnt(0)
	s_add_i32 s34, s34, 1
	s_cmpk_eq_i32 s34, 0x200
	s_barrier
	s_cbranch_scc1 .LBB0_544

.Lrb_done:
	v_add_co_u32_e64 v16, s[26:27], s34, 8
	s_waitcnt lgkmcnt(0)
	s_barrier
	ds_read2_b32 v[170:171], v231 offset1:16
	ds_read2_b32 v[172:173], v231 offset0:32 offset1:48
	ds_read2_b32 v[174:175], v230 offset1:16
	ds_read2_b32 v[176:177], v230 offset0:32 offset1:48
	ds_read2_b32 v[178:179], v91 offset1:16
	ds_read2_b32 v[180:181], v91 offset0:32 offset1:48
	ds_read2_b32 v[186:187], v234 offset1:16
	ds_read2_b32 v[188:189], v234 offset0:32 offset1:48
	ds_read2_b32 v[190:191], v233 offset1:16
	ds_read2_b32 v[192:193], v233 offset0:32 offset1:48
	ds_read2_b32 v[194:195], v93 offset1:16
	ds_read2_b32 v[196:197], v93 offset0:32 offset1:48
	v_readfirstlane_b32 s30, v16
	s_and_b64 s[28:29], s[26:27], exec
	s_cselect_b32 s28, s30, s34
	s_cselect_b32 s29, 7, 0x1ff
	s_sub_i32 s29, s29, s28
	s_and_b64 s[26:27], s[26:27], exec
	s_cselect_b32 s31, 0x4000, 0
	s_and_b64 s[26:27], s[64:65], exec
	s_cselect_b32 s26, s28, s29
	s_lshl_b32 s35, s26, 5
	s_add_i32 s35, s35, s31
	s_waitcnt lgkmcnt(6)
	v_add_f32_e32 v206, -1.0, v170
	v_mul_f32_e32 v182, v127, v174
	v_fma_f32 v206, v128, v206, 1.0
	v_mul_f32_e32 v202, v182, v182
	v_mul_f32_e32 v174, v174, v206
	v_mul_f32_e32 v178, v178, v174
	v_mul_f32_e32 v204, v129, v178
	v_add_f32_e32 v206, -1.0, v171
	v_mul_f32_e32 v183, v130, v175
	v_fma_f32 v206, v131, v206, 1.0
	v_fmac_f32_e32 v202, v183, v183
	v_mul_f32_e32 v175, v175, v206
	v_mul_f32_e32 v179, v179, v175
	v_fmac_f32_e32 v204, v132, v179
	v_add_f32_e32 v206, -1.0, v172
	v_mul_f32_e32 v184, v133, v176
	v_fma_f32 v206, v134, v206, 1.0
	v_fmac_f32_e32 v202, v184, v184
	v_mul_f32_e32 v176, v176, v206
	v_mul_f32_e32 v180, v180, v176
	v_fmac_f32_e32 v204, v135, v180
	v_add_f32_e32 v206, -1.0, v173
	v_mul_f32_e32 v185, v136, v177
	v_fma_f32 v206, v137, v206, 1.0
	v_fmac_f32_e32 v202, v185, v185
	v_mul_f32_e32 v177, v177, v206
	v_mul_f32_e32 v181, v181, v177
	v_fmac_f32_e32 v204, v138, v181
	ds_write2_b32 v230, v174, v175 offset1:16
	ds_write2_b32 v230, v176, v177 offset0:32 offset1:48
	s_waitcnt lgkmcnt(2)
	v_add_f32_e32 v207, -1.0, v186
	v_mul_f32_e32 v198, v127, v190
	v_fma_f32 v207, v128, v207, 1.0
	v_mul_f32_e32 v203, v198, v198
	v_mul_f32_e32 v190, v190, v207
	v_mul_f32_e32 v194, v194, v190
	v_mul_f32_e32 v205, v129, v194
	v_add_f32_e32 v207, -1.0, v187
	v_mul_f32_e32 v199, v130, v191
	v_fma_f32 v207, v131, v207, 1.0
	v_fmac_f32_e32 v203, v199, v199
	v_mul_f32_e32 v191, v191, v207
	v_mul_f32_e32 v195, v195, v191
	v_fmac_f32_e32 v205, v132, v195
	v_add_f32_e32 v207, -1.0, v188
	v_mul_f32_e32 v200, v133, v192
	v_fma_f32 v207, v134, v207, 1.0
	v_fmac_f32_e32 v203, v200, v200
	v_mul_f32_e32 v192, v192, v207
	v_mul_f32_e32 v196, v196, v192
	v_fmac_f32_e32 v205, v135, v196
	v_add_f32_e32 v207, -1.0, v189
	v_mul_f32_e32 v201, v136, v193
	v_fma_f32 v207, v137, v207, 1.0
	v_fmac_f32_e32 v203, v201, v201
	v_mul_f32_e32 v193, v193, v207
	v_mul_f32_e32 v197, v197, v193
	v_fmac_f32_e32 v205, v138, v197
	ds_write2_b32 v233, v190, v191 offset1:16
	ds_write2_b32 v233, v192, v193 offset0:32 offset1:48
	s_nop 1
	v_add_f32_dpp v202, v202, v202 quad_perm:[1,0,3,2] row_mask:0xf bank_mask:0xf bound_ctrl:1
	v_add_f32_dpp v203, v203, v203 quad_perm:[1,0,3,2] row_mask:0xf bank_mask:0xf bound_ctrl:1
	v_add_f32_dpp v204, v204, v204 quad_perm:[1,0,3,2] row_mask:0xf bank_mask:0xf bound_ctrl:1
	v_add_f32_dpp v205, v205, v205 quad_perm:[1,0,3,2] row_mask:0xf bank_mask:0xf bound_ctrl:1
	v_add_f32_dpp v202, v202, v202 quad_perm:[2,3,0,1] row_mask:0xf bank_mask:0xf bound_ctrl:1
	v_add_f32_dpp v203, v203, v203 quad_perm:[2,3,0,1] row_mask:0xf bank_mask:0xf bound_ctrl:1
	v_add_f32_dpp v204, v204, v204 quad_perm:[2,3,0,1] row_mask:0xf bank_mask:0xf bound_ctrl:1
	v_add_f32_dpp v205, v205, v205 quad_perm:[2,3,0,1] row_mask:0xf bank_mask:0xf bound_ctrl:1
	v_add_f32_dpp v202, v202, v202 row_half_mirror row_mask:0xf bank_mask:0xf bound_ctrl:1
	v_add_f32_dpp v203, v203, v203 row_half_mirror row_mask:0xf bank_mask:0xf bound_ctrl:1
	v_add_f32_dpp v204, v204, v204 row_half_mirror row_mask:0xf bank_mask:0xf bound_ctrl:1
	v_add_f32_dpp v205, v205, v205 row_half_mirror row_mask:0xf bank_mask:0xf bound_ctrl:1
	v_add_f32_dpp v202, v202, v202 row_mirror row_mask:0xf bank_mask:0xf bound_ctrl:1
	v_add_f32_dpp v203, v203, v203 row_mirror row_mask:0xf bank_mask:0xf bound_ctrl:1
	v_add_f32_dpp v204, v204, v204 row_mirror row_mask:0xf bank_mask:0xf bound_ctrl:1
	v_add_f32_dpp v205, v205, v205 row_mirror row_mask:0xf bank_mask:0xf bound_ctrl:1
	v_sqrt_f32_e32 v202, v202
	v_sqrt_f32_e32 v203, v203
	s_nop 0
	v_max_f32_e32 v202, 0x2b8cbccc, v202
	v_max_f32_e32 v203, 0x2b8cbccc, v203
	v_rcp_f32_e32 v202, v202
	v_rcp_f32_e32 v203, v203
	s_nop 0
	v_mul_f32_e32 v182, v182, v202
	v_mul_f32_e32 v183, v183, v202
	v_mul_f32_e32 v184, v184, v202
	v_mul_f32_e32 v185, v185, v202
	v_mul_f32_e32 v170, v170, v182
	v_mul_f32_e32 v171, v171, v183
	v_mul_f32_e32 v172, v172, v184
	v_mul_f32_e32 v173, v173, v185
	ds_write2_b32 v232, v182, v183 offset1:16
	ds_write2_b32 v232, v184, v185 offset0:32 offset1:48
	ds_write2_b32 v231, v170, v171 offset1:16
	ds_write2_b32 v231, v172, v173 offset0:32 offset1:48
	v_mul_f32_e32 v198, v198, v203
	v_mul_f32_e32 v199, v199, v203
	v_mul_f32_e32 v200, v200, v203
	v_mul_f32_e32 v201, v201, v203
	v_mul_f32_e32 v186, v186, v198
	v_mul_f32_e32 v187, v187, v199
	v_mul_f32_e32 v188, v188, v200
	v_mul_f32_e32 v189, v189, v201
	ds_write2_b32 v235, v198, v199 offset1:16
	ds_write2_b32 v235, v200, v201 offset0:32 offset1:48
	ds_write2_b32 v234, v186, v187 offset1:16
	ds_write2_b32 v234, v188, v189 offset0:32 offset1:48
	s_and_saveexec_b64 s[26:27], s[16:17]
	s_cbranch_execz .LBB0_492
	v_add_u32_e32 v62, s35, v87
	v_ashrrev_i32_e32 v63, 31, v62
	v_lshlrev_b64 v[62:63], 5, v[62:63]
	v_lshl_add_u64 v[62:63], s[78:79], 0, v[62:63]
	global_store_dword v[62:63], v204, off
	v_add_u32_e32 v62, s35, v92
	v_ashrrev_i32_e32 v63, 31, v62
	v_lshlrev_b64 v[62:63], 5, v[62:63]
	v_lshl_add_u64 v[62:63], s[78:79], 0, v[62:63]
	global_store_dword v[62:63], v205, off

.Lrs_post:
	s_waitcnt lgkmcnt(0)
	s_barrier
	ds_read_b128 v[60:63], v101
	ds_read_b128 v[64:67], v101 offset:16
	ds_read_b128 v[68:71], v101 offset:32
	ds_read_b128 v[162:165], v101 offset:48
	s_lshl_b32 s26, s35, 10
	s_mov_b32 s27, 0
	v_lshl_add_u64 v[170:171], v[236:237], 0, s[26:27]
	s_waitcnt lgkmcnt(2)
	v_add_f32_e32 v60, v60, v61
	v_add_f32_e32 v62, v62, v63
	v_add_f32_e32 v64, v64, v65
	v_add_f32_e32 v66, v66, v67
	v_add_f32_e32 v60, v60, v62
	v_add_f32_e32 v64, v64, v66
	s_waitcnt lgkmcnt(0)
	v_add_f32_e32 v68, v68, v69
	v_add_f32_e32 v70, v70, v71
	v_add_f32_e32 v162, v162, v163
	v_add_f32_e32 v164, v164, v165
	v_add_f32_e32 v68, v68, v70
	v_add_f32_e32 v162, v162, v164
	v_add_f32_e32 v60, v60, v64
	v_add_f32_e32 v68, v68, v162
	v_add_f32_e32 v60, v60, v68
	s_nop 1
	v_mov_b32_dpp v61, v60 quad_perm:[1,0,3,2] row_mask:0xf bank_mask:0xf bound_ctrl:1
	s_nop 0
	v_cvt_pk_bf16_f32 v16, v60, v61
	s_mov_b32 s26, 0x55555555
	s_mov_b32 s27, 0x55555555
	s_and_b64 exec, exec, s[26:27]
	global_atomic_pk_add_bf16 v[170:171], v16, off
	s_mov_b64 exec, -1
	s_andn2_b64 vcc, exec, s[28:29]
	s_cbranch_vccnz .LBB0_423
	s_waitcnt vmcnt(1)
	v_lshlrev_b32_e32 v60, 16, v20
	v_and_b32_e32 v61, 0xffff0000, v20
	v_lshlrev_b32_e32 v62, 16, v21
	v_and_b32_e32 v63, 0xffff0000, v21
	v_lshlrev_b32_e32 v64, 16, v22
	v_and_b32_e32 v65, 0xffff0000, v22
	v_lshlrev_b32_e32 v66, 16, v23
	v_and_b32_e32 v67, 0xffff0000, v23
	ds_write_b128 v149, v[60:63]
	ds_write_b128 v149, v[64:67] offset:16
	v_lshlrev_b32_e32 v162, 16, v52
	v_and_b32_e32 v163, 0xffff0000, v52
	v_lshlrev_b32_e32 v164, 16, v53
	v_and_b32_e32 v165, 0xffff0000, v53
	v_lshlrev_b32_e32 v166, 16, v54
	v_and_b32_e32 v167, 0xffff0000, v54
	v_lshlrev_b32_e32 v168, 16, v55
	v_and_b32_e32 v169, 0xffff0000, v55
	ds_write_b128 v150, v[162:165]
	ds_write_b128 v150, v[166:169] offset:16
	ds_write_b128 v156, v[28:31]
	ds_write_b128 v157, v[0:3]
	s_and_saveexec_b64 s[26:27], s[14:15]
	s_cbranch_execz .Lrc_skip
	v_lshlrev_b32_e32 v60, 16, v48
	v_and_b32_e32 v61, 0xffff0000, v48
	v_lshlrev_b32_e32 v62, 16, v49
	v_and_b32_e32 v63, 0xffff0000, v49
	v_lshlrev_b32_e32 v64, 16, v50
	v_and_b32_e32 v65, 0xffff0000, v50
	v_lshlrev_b32_e32 v66, 16, v51
	v_and_b32_e32 v67, 0xffff0000, v51
	ds_write_b128 v151, v[60:63]
	ds_write_b128 v151, v[64:67] offset:16
